# LR2 layer-1 value-mix GEMM: bias, v and v_first operands of an item fetched once ahead of the fragment prefetch, sections run without vmcnt waits
# baseline (speedup 1.0000x reference)
.LBB0_2048:
	v_readlane_b32 s0, v254, 29
	v_readlane_b32 s1, v254, 30
	s_andn2_b64 vcc, exec, s[0:1]
	s_cbranch_vccnz .LBB0_2054
	s_add_i32 s0, s91, 0x20100
	v_mov_b32_e32 v0, s0
	ds_read_b32 v0, v0
	s_add_i32 s1, s91, 0x20104
	v_readlane_b32 s2, v254, 20
	s_cmpk_gt_i32 s2, 0x20ff
	v_readlane_b32 s3, v254, 21
	s_waitcnt lgkmcnt(0)
	v_readfirstlane_b32 s0, v0
	v_mov_b32_e32 v0, s1
	ds_read_b32 v0, v0
	s_waitcnt lgkmcnt(0)
	v_readfirstlane_b32 s1, v0
	s_cbranch_scc1 .LBB0_2054
	s_mul_i32 s2, s88, 0x2100000
	v_readlane_b32 s12, v254, 32
	v_readlane_b32 s13, v254, 33
	s_add_u32 s2, s12, s2
	s_addc_u32 s3, s13, 0
	s_add_u32 s4, s12, 0x10800000
	v_readlane_b32 s6, v254, 20
	s_addc_u32 s5, s13, 0
	s_mov_b32 s10, s6
	s_ashr_i32 s6, s6, 31
	s_lshr_b32 s6, s6, 28
	v_readlane_b32 s7, v254, 21
	s_add_i32 s6, s10, s6
	s_and_b32 s7, s6, 0x3fffff0
	s_lshl_b32 s6, s6, 1
	v_readlane_b32 s14, v254, 34
	s_andn2_b32 s6, s6, 31
	v_readlane_b32 s15, v254, 35
	v_or_b32_e32 v4, s6, v134
	s_sub_i32 s8, s10, s7
	v_mov_b64_e32 v[0:1], s[14:15]
	v_mad_i64_i32 v[2:3], s[6:7], v4, s95, v[0:1]
	v_or_b32_e32 v4, 16, v4
	v_and_b32_e32 v152, 48, v164
	v_mad_i64_i32 v[0:1], s[6:7], v4, s95, v[0:1]
	v_lshl_or_b32 v16, s8, 6, v134
	v_lshl_add_u64 v[8:9], s[12:13], 0, v[152:153]
	s_mov_b64 s[6:7], 0x14a50000
	v_ashrrev_i32_e32 v17, 31, v16
	v_lshl_add_u64 v[56:57], v[8:9], 0, s[6:7]
	v_lshlrev_b64 v[8:9], 6, v[16:17]
	v_or_b32_e32 v10, 16, v16
	v_or_b32_e32 v18, 32, v16
	v_or_b32_e32 v16, 48, v16
	v_ashrrev_i32_e32 v11, 31, v10
	v_ashrrev_i32_e32 v19, 31, v18
	v_ashrrev_i32_e32 v17, 31, v16
	v_lshlrev_b64 v[10:11], 6, v[10:11]
	v_lshlrev_b64 v[18:19], 6, v[18:19]
	v_lshlrev_b64 v[16:17], 6, v[16:17]
	v_lshl_add_u64 v[2:3], v[2:3], 0, v[152:153]
	v_lshl_add_u64 v[4:5], v[0:1], 0, v[152:153]
	v_lshl_add_u64 v[8:9], v[56:57], 0, v[8:9]
	s_waitcnt vmcnt(0)
	v_lshl_add_u64 v[12:13], v[56:57], 0, v[10:11]
	v_lshl_add_u64 v[18:19], v[56:57], 0, v[18:19]
	v_lshl_add_u64 v[20:21], v[56:57], 0, v[16:17]
	global_load_dwordx4 v[0:3], v[2:3], off offset:832
	s_nop 0
	global_load_dwordx4 v[4:7], v[4:5], off offset:832
	s_nop 0
	global_load_dwordx4 v[8:11], v[8:9], off
	s_nop 0
	global_load_dwordx4 v[12:15], v[12:13], off
	s_nop 0
	global_load_dwordx4 v[16:19], v[18:19], off
	s_nop 0
	global_load_dwordx4 v[20:23], v[20:21], off
	v_readlane_b32 s6, v254, 22
	v_lshrrev_b32_e32 v24, 2, v164
	s_lshl_b32 s9, s6, 6
	v_and_b32_e32 v78, 12, v24
	v_lshl_add_u64 v[58:59], s[14:15], 0, v[152:153]
	s_lshl_b32 s8, s10, 6
	v_or_b32_e32 v79, s9, v134
	s_mov_b32 s11, s10
	v_readlane_b32 s7, v254, 23
	s_waitcnt vmcnt(0)
	s_branch .LBB0_2052
.LBB0_2051:
	s_ashr_i32 s12, s11, 31
	s_lshr_b32 s12, s12, 28
	s_add_i32 s11, s11, s12
	s_ashr_i32 s11, s11, 4
	v_add_u32_e32 v60, s8, v78
	s_lshl_b32 s12, s11, 10
	v_subrev_u32_e32 v64, s12, v60
	v_lshl_or_b32 v66, s11, 5, v134
	v_ashrrev_i32_e32 v65, 31, v64
	v_ashrrev_i32_e32 v67, 31, v66
	v_lshl_add_u64 v[60:61], v[64:65], 2, s[0:1]
	v_lshlrev_b64 v[70:71], 10, v[66:67]
	v_lshl_add_u64 v[62:63], v[70:71], 0, v[64:65]
	v_lshlrev_b64 v[62:63], 1, v[62:63]
	v_lshl_add_u64 v[68:69], s[2:3], 0, v[62:63]
	v_lshl_add_u64 v[62:63], s[4:5], 0, v[62:63]
	v_add_u32_e32 v62, 16, v64
	s_add_i32 s8, s8, s9
	s_and_b64 vcc, exec, s[6:7]
	s_mov_b32 s11, s10
	v_add_f32_e32 v52, v52, v96
	v_add_f32_e32 v53, v53, v97
	v_add_f32_e32 v54, v54, v98
	v_add_f32_e32 v55, v55, v99
	v_mul_f32_e32 v52, 0xbfb8aa3b, v52
	v_mul_f32_e32 v53, 0xbfb8aa3b, v53
	v_mul_f32_e32 v54, 0xbfb8aa3b, v54
	v_mul_f32_e32 v55, 0xbfb8aa3b, v55
	v_exp_f32_e32 v63, v52
	v_exp_f32_e32 v67, v53
	v_exp_f32_e32 v72, v54
	v_exp_f32_e32 v73, v55
	v_cvt_f32_f16_e32 v52, v112
	v_cvt_f32_f16_sdwa v53, v112 dst_sel:DWORD dst_unused:UNUSED_PAD src0_sel:WORD_1
	v_cvt_f32_f16_sdwa v74, v136 dst_sel:DWORD dst_unused:UNUSED_PAD src0_sel:WORD_1
	v_cvt_f32_f16_e32 v75, v136
	v_cvt_f32_f16_e32 v54, v113
	v_cvt_f32_f16_sdwa v55, v113 dst_sel:DWORD dst_unused:UNUSED_PAD src0_sel:WORD_1
	v_cvt_f32_f16_sdwa v84, v137 dst_sel:DWORD dst_unused:UNUSED_PAD src0_sel:WORD_1
	v_cvt_f32_f16_e32 v80, v137
	v_add_f32_e32 v63, 1.0, v63
	v_add_f32_e32 v67, 1.0, v67
	v_add_f32_e32 v76, 1.0, v72
	v_add_f32_e32 v77, 1.0, v73
	v_sub_f32_e32 v72, v75, v52
	v_sub_f32_e32 v73, v74, v53
	v_rcp_f32_e32 v74, v63
	v_rcp_f32_e32 v76, v76
	v_rcp_f32_e32 v77, v77
	v_rcp_f32_e32 v75, v67
	v_sub_f32_e32 v80, v80, v54
	v_sub_f32_e32 v81, v84, v55
	v_pk_fma_f32 v[54:55], v[76:77], v[80:81], v[54:55]
	v_pk_fma_f32 v[52:53], v[74:75], v[72:73], v[52:53]
	v_cvt_pk_f16_f32 v55, v54, v55
	v_cvt_pk_f16_f32 v54, v52, v53
	global_store_dwordx2 v[68:69], v[54:55], off
	v_ashrrev_i32_e32 v63, 31, v62
	v_lshl_add_u64 v[52:53], v[70:71], 0, v[62:63]
	v_lshl_add_u64 v[52:53], v[52:53], 1, s[4:5]
	v_cvt_f32_f16_e32 v80, v114
	v_cvt_f32_f16_sdwa v81, v114 dst_sel:DWORD dst_unused:UNUSED_PAD src0_sel:WORD_1
	v_cvt_f32_f16_e32 v82, v115
	v_cvt_f32_f16_sdwa v83, v115 dst_sel:DWORD dst_unused:UNUSED_PAD src0_sel:WORD_1
	v_add_u32_e32 v54, 32, v64
	v_add_f32_e32 v48, v48, v100
	v_add_f32_e32 v49, v49, v101
	v_add_f32_e32 v50, v50, v102
	v_add_f32_e32 v51, v51, v103
	v_mul_f32_e32 v48, 0xbfb8aa3b, v48
	v_mul_f32_e32 v49, 0xbfb8aa3b, v49
	v_mul_f32_e32 v50, 0xbfb8aa3b, v50
	v_mul_f32_e32 v51, 0xbfb8aa3b, v51
	v_cvt_f32_f16_sdwa v55, v138 dst_sel:DWORD dst_unused:UNUSED_PAD src0_sel:WORD_1
	v_cvt_f32_f16_e32 v52, v138
	v_cvt_f32_f16_sdwa v67, v139 dst_sel:DWORD dst_unused:UNUSED_PAD src0_sel:WORD_1
	v_cvt_f32_f16_e32 v74, v139
	v_exp_f32_e32 v53, v48
	v_exp_f32_e32 v75, v49
	v_exp_f32_e32 v50, v50
	v_exp_f32_e32 v51, v51
	v_sub_f32_e32 v48, v52, v80
	v_sub_f32_e32 v49, v55, v81
	v_add_f32_e32 v52, 1.0, v53
	v_add_f32_e32 v55, 1.0, v75
	v_add_f32_e32 v53, 1.0, v50
	v_add_f32_e32 v51, 1.0, v51
	v_rcp_f32_e32 v50, v52
	v_rcp_f32_e32 v52, v53
	v_rcp_f32_e32 v53, v51
	v_rcp_f32_e32 v51, v55
	v_sub_f32_e32 v74, v74, v82
	v_sub_f32_e32 v75, v67, v83
	v_pk_fma_f32 v[52:53], v[52:53], v[74:75], v[82:83]
	v_pk_fma_f32 v[48:49], v[50:51], v[48:49], v[80:81]
	v_cvt_pk_f16_f32 v51, v52, v53
	v_cvt_pk_f16_f32 v50, v48, v49
	global_store_dwordx2 v[68:69], v[50:51], off offset:32
	v_ashrrev_i32_e32 v55, 31, v54
	v_lshl_add_u64 v[52:53], v[70:71], 0, v[54:55]
	v_lshl_add_u64 v[52:53], v[52:53], 1, s[4:5]
	v_cvt_f32_f16_e32 v80, v116
	v_cvt_f32_f16_sdwa v81, v116 dst_sel:DWORD dst_unused:UNUSED_PAD src0_sel:WORD_1
	v_cvt_f32_f16_e32 v72, v117
	v_cvt_f32_f16_sdwa v73, v117 dst_sel:DWORD dst_unused:UNUSED_PAD src0_sel:WORD_1
	v_add_u32_e32 v52, 48, v64
	v_add_f32_e32 v44, v44, v104
	v_add_f32_e32 v45, v45, v105
	v_add_f32_e32 v46, v46, v106
	v_add_f32_e32 v47, v47, v107
	v_mul_f32_e32 v44, 0xbfb8aa3b, v44
	v_mul_f32_e32 v45, 0xbfb8aa3b, v45
	v_mul_f32_e32 v46, 0xbfb8aa3b, v46
	v_mul_f32_e32 v47, 0xbfb8aa3b, v47
	v_cvt_f32_f16_sdwa v48, v140 dst_sel:DWORD dst_unused:UNUSED_PAD src0_sel:WORD_1
	v_cvt_f32_f16_e32 v49, v140
	v_exp_f32_e32 v53, v44
	v_exp_f32_e32 v67, v45
	v_exp_f32_e32 v46, v46
	v_exp_f32_e32 v47, v47
	v_cvt_f32_f16_sdwa v51, v141 dst_sel:DWORD dst_unused:UNUSED_PAD src0_sel:WORD_1
	v_cvt_f32_f16_e32 v50, v141
	v_sub_f32_e32 v44, v49, v80
	v_sub_f32_e32 v45, v48, v81
	v_add_f32_e32 v48, 1.0, v53
	v_add_f32_e32 v53, 1.0, v67
	v_add_f32_e32 v49, 1.0, v46
	v_add_f32_e32 v47, 1.0, v47
	v_rcp_f32_e32 v46, v48
	v_rcp_f32_e32 v48, v49
	v_rcp_f32_e32 v49, v47
	v_rcp_f32_e32 v47, v53
	v_sub_f32_e32 v50, v50, v72
	v_sub_f32_e32 v51, v51, v73
	v_pk_fma_f32 v[48:49], v[48:49], v[50:51], v[72:73]
	v_pk_fma_f32 v[44:45], v[46:47], v[44:45], v[80:81]
	v_cvt_pk_f16_f32 v47, v48, v49
	v_cvt_pk_f16_f32 v46, v44, v45
	global_store_dwordx2 v[68:69], v[46:47], off offset:64
	v_ashrrev_i32_e32 v53, 31, v52
	v_lshl_add_u64 v[44:45], v[70:71], 0, v[52:53]
	v_lshl_add_u64 v[44:45], v[44:45], 1, s[4:5]
	v_or_b32_e32 v44, 16, v66
	v_cvt_f32_f16_e32 v66, v118
	v_cvt_f32_f16_sdwa v67, v118 dst_sel:DWORD dst_unused:UNUSED_PAD src0_sel:WORD_1
	v_cvt_f32_f16_e32 v70, v119
	v_cvt_f32_f16_sdwa v71, v119 dst_sel:DWORD dst_unused:UNUSED_PAD src0_sel:WORD_1
	v_ashrrev_i32_e32 v45, 31, v44
	v_lshlrev_b64 v[44:45], 10, v[44:45]
	v_add_f32_e32 v40, v40, v108
	v_add_f32_e32 v41, v41, v109
	v_add_f32_e32 v42, v42, v110
	v_add_f32_e32 v43, v43, v111
	v_mul_f32_e32 v40, 0xbfb8aa3b, v40
	v_mul_f32_e32 v41, 0xbfb8aa3b, v41
	v_mul_f32_e32 v42, 0xbfb8aa3b, v42
	v_mul_f32_e32 v43, 0xbfb8aa3b, v43
	v_cvt_f32_f16_sdwa v46, v142 dst_sel:DWORD dst_unused:UNUSED_PAD src0_sel:WORD_1
	v_cvt_f32_f16_e32 v47, v142
	v_cvt_f32_f16_sdwa v49, v143 dst_sel:DWORD dst_unused:UNUSED_PAD src0_sel:WORD_1
	v_cvt_f32_f16_e32 v48, v143
	v_exp_f32_e32 v50, v40
	v_exp_f32_e32 v51, v41
	v_exp_f32_e32 v42, v42
	v_exp_f32_e32 v43, v43
	v_sub_f32_e32 v40, v47, v66
	v_sub_f32_e32 v41, v46, v67
	v_add_f32_e32 v46, 1.0, v50
	v_add_f32_e32 v50, 1.0, v51
	v_add_f32_e32 v47, 1.0, v42
	v_add_f32_e32 v43, 1.0, v43
	v_rcp_f32_e32 v42, v46
	v_rcp_f32_e32 v46, v47
	v_rcp_f32_e32 v47, v43
	v_rcp_f32_e32 v43, v50
	v_sub_f32_e32 v48, v48, v70
	v_sub_f32_e32 v49, v49, v71
	v_pk_fma_f32 v[46:47], v[46:47], v[48:49], v[70:71]
	v_pk_fma_f32 v[40:41], v[42:43], v[40:41], v[66:67]
	v_cvt_pk_f16_f32 v43, v46, v47
	v_cvt_pk_f16_f32 v42, v40, v41
	v_lshl_add_u64 v[40:41], v[44:45], 0, v[64:65]
	global_store_dwordx2 v[68:69], v[42:43], off offset:96
	v_lshlrev_b64 v[42:43], 1, v[40:41]
	v_lshl_add_u64 v[40:41], s[2:3], 0, v[42:43]
	v_lshl_add_u64 v[42:43], s[4:5], 0, v[42:43]
	s_nop 0
	v_add_f32_e32 v46, v36, v96
	v_add_f32_e32 v47, v37, v97
	v_add_f32_e32 v48, v38, v98
	v_add_f32_e32 v49, v39, v99
	v_cvt_f32_f16_e32 v38, v121
	v_cvt_f32_f16_sdwa v39, v121 dst_sel:DWORD dst_unused:UNUSED_PAD src0_sel:WORD_1
	v_cvt_f32_f16_sdwa v51, v145 dst_sel:DWORD dst_unused:UNUSED_PAD src0_sel:WORD_1
	v_cvt_f32_f16_e32 v66, v145
	v_mul_f32_e32 v43, 0xbfb8aa3b, v46
	v_mul_f32_e32 v46, 0xbfb8aa3b, v47
	v_mul_f32_e32 v47, 0xbfb8aa3b, v48
	v_mul_f32_e32 v48, 0xbfb8aa3b, v49
	v_cvt_f32_f16_e32 v36, v120
	v_cvt_f32_f16_sdwa v37, v120 dst_sel:DWORD dst_unused:UNUSED_PAD src0_sel:WORD_1
	v_cvt_f32_f16_sdwa v50, v144 dst_sel:DWORD dst_unused:UNUSED_PAD src0_sel:WORD_1
	v_exp_f32_e32 v49, v43
	v_exp_f32_e32 v46, v46
	v_exp_f32_e32 v47, v47
	v_exp_f32_e32 v48, v48
	v_cvt_f32_f16_e32 v42, v144
	v_sub_f32_e32 v43, v50, v37
	v_add_f32_e32 v49, 1.0, v49
	v_add_f32_e32 v50, 1.0, v46
	v_add_f32_e32 v47, 1.0, v47
	v_add_f32_e32 v67, 1.0, v48
	v_rcp_f32_e32 v46, v49
	v_rcp_f32_e32 v48, v47
	v_rcp_f32_e32 v49, v67
	v_rcp_f32_e32 v47, v50
	v_sub_f32_e32 v42, v42, v36
	v_sub_f32_e32 v50, v66, v38
	v_sub_f32_e32 v51, v51, v39
	v_pk_fma_f32 v[38:39], v[48:49], v[50:51], v[38:39]
	v_pk_fma_f32 v[36:37], v[46:47], v[42:43], v[36:37]
	v_cvt_pk_f16_f32 v39, v38, v39
	v_cvt_pk_f16_f32 v38, v36, v37
	global_store_dwordx2 v[40:41], v[38:39], off
	v_lshl_add_u64 v[36:37], v[44:45], 0, v[62:63]
	v_lshl_add_u64 v[36:37], v[36:37], 1, s[4:5]
	s_nop 0
	v_cvt_f32_f16_e32 v42, v122
	v_cvt_f32_f16_sdwa v43, v122 dst_sel:DWORD dst_unused:UNUSED_PAD src0_sel:WORD_1
	v_cvt_f32_f16_e32 v50, v123
	v_cvt_f32_f16_sdwa v51, v123 dst_sel:DWORD dst_unused:UNUSED_PAD src0_sel:WORD_1
	v_add_f32_e32 v32, v32, v100
	v_add_f32_e32 v33, v33, v101
	v_add_f32_e32 v34, v34, v102
	v_add_f32_e32 v35, v35, v103
	v_mul_f32_e32 v32, 0xbfb8aa3b, v32
	v_mul_f32_e32 v33, 0xbfb8aa3b, v33
	v_mul_f32_e32 v34, 0xbfb8aa3b, v34
	v_mul_f32_e32 v35, 0xbfb8aa3b, v35
	v_cvt_f32_f16_sdwa v46, v146 dst_sel:DWORD dst_unused:UNUSED_PAD src0_sel:WORD_1
	v_cvt_f32_f16_e32 v38, v146
	v_cvt_f32_f16_sdwa v47, v147 dst_sel:DWORD dst_unused:UNUSED_PAD src0_sel:WORD_1
	v_cvt_f32_f16_e32 v48, v147
	v_exp_f32_e32 v39, v32
	v_exp_f32_e32 v49, v33
	v_exp_f32_e32 v34, v34
	v_exp_f32_e32 v35, v35
	v_sub_f32_e32 v32, v38, v42
	v_sub_f32_e32 v33, v46, v43
	v_add_f32_e32 v38, 1.0, v39
	v_add_f32_e32 v46, 1.0, v49
	v_add_f32_e32 v39, 1.0, v34
	v_add_f32_e32 v35, 1.0, v35
	v_rcp_f32_e32 v34, v38
	v_rcp_f32_e32 v38, v39
	v_rcp_f32_e32 v39, v35
	v_rcp_f32_e32 v35, v46
	v_sub_f32_e32 v46, v48, v50
	v_sub_f32_e32 v47, v47, v51
	v_pk_fma_f32 v[38:39], v[38:39], v[46:47], v[50:51]
	v_pk_fma_f32 v[32:33], v[34:35], v[32:33], v[42:43]
	v_cvt_pk_f16_f32 v35, v38, v39
	v_cvt_pk_f16_f32 v34, v32, v33
	global_store_dwordx2 v[40:41], v[34:35], off offset:32
	v_lshl_add_u64 v[38:39], v[44:45], 0, v[54:55]
	v_lshl_add_u64 v[38:39], v[38:39], 1, s[4:5]
	s_nop 0
	v_cvt_f32_f16_e32 v46, v124
	v_cvt_f32_f16_sdwa v47, v124 dst_sel:DWORD dst_unused:UNUSED_PAD src0_sel:WORD_1
	v_cvt_f32_f16_e32 v36, v125
	v_cvt_f32_f16_sdwa v37, v125 dst_sel:DWORD dst_unused:UNUSED_PAD src0_sel:WORD_1
	v_add_f32_e32 v28, v28, v104
	v_add_f32_e32 v29, v29, v105
	v_add_f32_e32 v30, v30, v106
	v_add_f32_e32 v31, v31, v107
	v_mul_f32_e32 v28, 0xbfb8aa3b, v28
	v_mul_f32_e32 v29, 0xbfb8aa3b, v29
	v_mul_f32_e32 v30, 0xbfb8aa3b, v30
	v_mul_f32_e32 v31, 0xbfb8aa3b, v31
	v_cvt_f32_f16_sdwa v32, v148 dst_sel:DWORD dst_unused:UNUSED_PAD src0_sel:WORD_1
	v_cvt_f32_f16_e32 v33, v148
	v_cvt_f32_f16_sdwa v35, v149 dst_sel:DWORD dst_unused:UNUSED_PAD src0_sel:WORD_1
	v_cvt_f32_f16_e32 v34, v149
	v_exp_f32_e32 v42, v28
	v_exp_f32_e32 v43, v29
	v_exp_f32_e32 v30, v30
	v_exp_f32_e32 v31, v31
	v_sub_f32_e32 v28, v33, v46
	v_sub_f32_e32 v29, v32, v47
	v_add_f32_e32 v32, 1.0, v42
	v_add_f32_e32 v42, 1.0, v43
	v_add_f32_e32 v33, 1.0, v30
	v_add_f32_e32 v31, 1.0, v31
	v_rcp_f32_e32 v30, v32
	v_rcp_f32_e32 v32, v33
	v_rcp_f32_e32 v33, v31
	v_rcp_f32_e32 v31, v42
	v_sub_f32_e32 v34, v34, v36
	v_sub_f32_e32 v35, v35, v37
	v_pk_fma_f32 v[32:33], v[32:33], v[34:35], v[36:37]
	v_pk_fma_f32 v[28:29], v[30:31], v[28:29], v[46:47]
	v_cvt_pk_f16_f32 v31, v32, v33
	v_cvt_pk_f16_f32 v30, v28, v29
	global_store_dwordx2 v[40:41], v[30:31], off offset:64
	v_lshl_add_u64 v[32:33], v[44:45], 0, v[52:53]
	v_lshl_add_u64 v[32:33], v[32:33], 1, s[4:5]
	v_cvt_f32_f16_e32 v34, v126
	v_cvt_f32_f16_sdwa v35, v126 dst_sel:DWORD dst_unused:UNUSED_PAD src0_sel:WORD_1
	v_cvt_f32_f16_e32 v36, v127
	v_cvt_f32_f16_sdwa v37, v127 dst_sel:DWORD dst_unused:UNUSED_PAD src0_sel:WORD_1
	v_add_f32_e32 v24, v24, v108
	v_add_f32_e32 v25, v25, v109
	v_add_f32_e32 v26, v26, v110
	v_add_f32_e32 v27, v27, v111
	v_mul_f32_e32 v24, 0xbfb8aa3b, v24
	v_mul_f32_e32 v25, 0xbfb8aa3b, v25
	v_mul_f32_e32 v26, 0xbfb8aa3b, v26
	v_mul_f32_e32 v27, 0xbfb8aa3b, v27
	v_cvt_f32_f16_sdwa v28, v150 dst_sel:DWORD dst_unused:UNUSED_PAD src0_sel:WORD_1
	v_cvt_f32_f16_e32 v29, v150
	v_cvt_f32_f16_sdwa v31, v151 dst_sel:DWORD dst_unused:UNUSED_PAD src0_sel:WORD_1
	v_cvt_f32_f16_e32 v30, v151
	v_exp_f32_e32 v32, v24
	v_exp_f32_e32 v33, v25
	v_exp_f32_e32 v26, v26
	v_exp_f32_e32 v27, v27
	v_sub_f32_e32 v24, v29, v34
	v_sub_f32_e32 v25, v28, v35
	v_add_f32_e32 v28, 1.0, v32
	v_add_f32_e32 v32, 1.0, v33
	v_add_f32_e32 v29, 1.0, v26
	v_add_f32_e32 v27, 1.0, v27
	v_rcp_f32_e32 v26, v28
	v_rcp_f32_e32 v28, v29
	v_rcp_f32_e32 v29, v27
	v_rcp_f32_e32 v27, v32
	v_sub_f32_e32 v30, v30, v36
	v_sub_f32_e32 v31, v31, v37
	v_pk_fma_f32 v[28:29], v[28:29], v[30:31], v[36:37]
	v_pk_fma_f32 v[24:25], v[26:27], v[24:25], v[34:35]
	v_cvt_pk_f16_f32 v27, v28, v29
	v_cvt_pk_f16_f32 v26, v24, v25
	global_store_dwordx2 v[40:41], v[26:27], off offset:96
	s_cbranch_vccnz .LBB0_2054
.LBB0_2052:
	v_readlane_b32 s6, v254, 22
	s_waitcnt vmcnt(11)
	v_mfma_f32_16x16x32_bf16 v[52:55], v[8:11], v[0:3], 0
	s_add_i32 s10, s11, s6
	v_readlane_b32 s7, v254, 23
	s_cmpk_gt_i32 s10, 0x20ff
	s_waitcnt vmcnt(10)
	v_mfma_f32_16x16x32_bf16 v[48:51], v[12:15], v[0:3], 0
	s_cselect_b64 s[6:7], -1, 0
	s_and_b64 vcc, exec, s[6:7]
	s_waitcnt vmcnt(9)
	v_mfma_f32_16x16x32_bf16 v[44:47], v[16:19], v[0:3], 0
	s_waitcnt vmcnt(8)
	v_mfma_f32_16x16x32_bf16 v[40:43], v[20:23], v[0:3], 0
	v_mfma_f32_16x16x32_bf16 v[36:39], v[8:11], v[4:7], 0
	v_mfma_f32_16x16x32_bf16 v[32:35], v[12:15], v[4:7], 0
	v_mfma_f32_16x16x32_bf16 v[28:31], v[16:19], v[4:7], 0
	v_mfma_f32_16x16x32_bf16 v[24:27], v[20:23], v[4:7], 0
	s_ashr_i32 s12, s11, 31
	s_lshr_b32 s12, s12, 28
	s_add_i32 s12, s11, s12
	s_ashr_i32 s12, s12, 4
	v_add_u32_e32 v86, s8, v78
	s_lshl_b32 s13, s12, 10
	v_subrev_u32_e32 v86, s13, v86
	v_lshl_or_b32 v88, s12, 5, v134
	v_ashrrev_i32_e32 v87, 31, v86
	v_ashrrev_i32_e32 v89, 31, v88
	v_lshl_add_u64 v[92:93], v[86:87], 2, s[0:1]
	v_lshlrev_b64 v[90:91], 10, v[88:89]
	v_lshl_add_u64 v[90:91], v[90:91], 0, v[86:87]
	v_lshlrev_b64 v[90:91], 1, v[90:91]
	v_lshl_add_u64 v[94:95], s[2:3], 0, v[90:91]
	v_lshl_add_u64 v[166:167], s[4:5], 0, v[90:91]
	s_mov_b64 s[12:13], 0x8000
	v_lshl_add_u64 v[168:169], v[94:95], 0, s[12:13]
	v_lshl_add_u64 v[170:171], v[166:167], 0, s[12:13]
	global_load_dwordx4 v[96:99], v[92:93], off
	global_load_dwordx4 v[100:103], v[92:93], off offset:64
	global_load_dwordx4 v[104:107], v[92:93], off offset:128
	global_load_dwordx4 v[108:111], v[92:93], off offset:192
	global_load_dwordx2 v[112:113], v[94:95], off
	global_load_dwordx2 v[136:137], v[166:167], off
	global_load_dwordx2 v[114:115], v[94:95], off offset:32
	global_load_dwordx2 v[138:139], v[166:167], off offset:32
	global_load_dwordx2 v[116:117], v[94:95], off offset:64
	global_load_dwordx2 v[140:141], v[166:167], off offset:64
	global_load_dwordx2 v[118:119], v[94:95], off offset:96
	global_load_dwordx2 v[142:143], v[166:167], off offset:96
	global_load_dwordx2 v[120:121], v[168:169], off
	global_load_dwordx2 v[144:145], v[170:171], off
	global_load_dwordx2 v[122:123], v[168:169], off offset:32
	global_load_dwordx2 v[146:147], v[170:171], off offset:32
	global_load_dwordx2 v[124:125], v[168:169], off offset:64
	global_load_dwordx2 v[148:149], v[170:171], off offset:64
	global_load_dwordx2 v[126:127], v[168:169], off offset:96
	global_load_dwordx2 v[150:151], v[170:171], off offset:96
	s_cbranch_vccnz .Lfv_nopf
	s_ashr_i32 s12, s10, 31
	s_lshr_b32 s12, s12, 28
	s_add_i32 s12, s10, s12
	s_ashr_i32 s14, s12, 4
	v_lshl_or_b32 v2, s14, 5, v134
	v_mad_i64_i32 v[0:1], s[12:13], v2, s95, v[58:59]
	v_or_b32_e32 v2, 16, v2
	v_mad_i64_i32 v[4:5], s[12:13], v2, s95, v[58:59]
	v_add_u32_e32 v8, s8, v79
	s_lshl_b32 s12, s14, 10
	v_subrev_u32_e32 v16, s12, v8
	v_ashrrev_i32_e32 v17, 31, v16
	v_lshlrev_b64 v[8:9], 6, v[16:17]
	v_add_u32_e32 v10, 16, v16
	v_add_u32_e32 v18, 32, v16
	v_add_u32_e32 v16, 48, v16
	v_ashrrev_i32_e32 v11, 31, v10
	v_ashrrev_i32_e32 v19, 31, v18
	v_ashrrev_i32_e32 v17, 31, v16
	v_lshlrev_b64 v[10:11], 6, v[10:11]
	v_lshlrev_b64 v[18:19], 6, v[18:19]
	v_lshlrev_b64 v[16:17], 6, v[16:17]
	v_lshl_add_u64 v[8:9], v[56:57], 0, v[8:9]
	v_lshl_add_u64 v[12:13], v[56:57], 0, v[10:11]
	v_lshl_add_u64 v[18:19], v[56:57], 0, v[18:19]
	v_lshl_add_u64 v[20:21], v[56:57], 0, v[16:17]
	global_load_dwordx4 v[0:3], v[0:1], off offset:832
	s_nop 0
	global_load_dwordx4 v[4:7], v[4:5], off offset:832
	s_nop 0
	global_load_dwordx4 v[8:11], v[8:9], off
	s_nop 0
	global_load_dwordx4 v[12:15], v[12:13], off
	s_nop 0
	global_load_dwordx4 v[16:19], v[18:19], off
	s_nop 0
	global_load_dwordx4 v[20:23], v[20:21], off
	s_waitcnt vmcnt(6)
	s_branch .LBB0_2051
.Lfv_nopf:
	s_waitcnt vmcnt(0)
	s_branch .LBB0_2051
.LBB0_2054:
	s_mov_b64 s[0:1], 0
